# stack: step-2 CKV rebalance + per-item pop issued before the item barrier (one barrier fewer per attention item) on top of the balanced conversion
# baseline (speedup 1.0000x reference)
;     DI unsigned char* ws() const { return (unsigned char*)gp(35); }
; DI int fresh_tid(const Params& P) { int t = P.tid; asm volatile("" : "+v"(t)); return t; }
; template <int TYPE>
; DI void attn_phase(const Params& P, int l, unsigned char* shm, const int rep, const bool cross = false) {
;     const int tid_ = fresh_tid(P);
;     unsigned char* ws = P.ws(); int* ctl = (int*)(ws + WS_CTL);
;     bf16_t* z = (bf16_t*)(ws + WS_Z); bf16_t* ckv = (bf16_t*)(ws + WS_H); bf16_t* cq = (bf16_t*)(ws + WS_CQ); bf16_t* o = (bf16_t*)(ws + WS_O);
;     int* sidx = (int*)(shm + ATT_IDX); float* tab = (float*)(shm + ATT_TAB);
;     for (;;) {
;         __syncthreads();
;         if (tid_ == 0) *sidx = atomicAdd(ctl + (l * 4 + (cross ? 3 : TYPE)) * 2 + rep, 1);
;         __syncthreads();
.LBB0_708:
	v_readlane_b32 s76, v242, 28
	s_movk_i32 s78, 0x1000
	s_movk_i32 s79, 0x1fff
	s_andn2_b64 vcc, exec, s[6:7]
	s_lshl_b32 s52, s8, 3
	v_readlane_b32 s77, v242, 29
	s_movk_i32 s82, 0x3fff
	s_cbranch_vccnz .LBB0_793
	v_readlane_b32 s4, v242, 39
	s_cmp_eq_u32 s4, 3
	s_cbranch_scc0 .LBB0_793
	v_mov_b32_e32 v146, v193
	v_mov_b32_e32 v0, s86
	s_waitcnt vmcnt(0)
	ds_read_b64 v[2:3], v0
	s_ashr_i32 s53, s52, 31
	s_ashr_i32 s9, s8, 31
	v_readlane_b32 s0, v242, 32
	v_readlane_b32 s1, v242, 33
	s_waitcnt lgkmcnt(0)
	v_readfirstlane_b32 s7, v2
	v_readfirstlane_b32 s6, v3
	s_add_u32 s12, s7, 0x4c80000
	s_addc_u32 s14, s6, 0
	s_add_u32 s15, s7, 0x1fc80000
	s_addc_u32 s20, s6, 0
	s_lshl_b64 s[54:55], s[52:53], 2
	v_cndmask_b32_e64 v156, v188, v189, s[0:1]
	s_add_u32 s0, s7, s54
	s_addc_u32 s1, s6, s55
	v_max_i32_e32 v0, 0xffffff01, v146
	s_add_u32 s56, s0, 0x29300000
	v_sub_u32_e32 v0, v0, v146
	s_addc_u32 s57, s1, 0
	s_lshl_b64 s[0:1], s[8:9], 2
	v_add_u32_e32 v0, 0x1ff, v0
	s_add_u32 s0, s7, s0
	v_lshrrev_b32_e32 v2, 9, v0
	s_addc_u32 s1, s6, s1
	v_add_u32_e32 v2, 1, v2
	s_add_u32 s58, s0, 0x29300040
	s_movk_i32 s0, 0x101
	v_and_b32_e32 v157, 0xfffffe, v2
	v_lshlrev_b32_e32 v159, 2, v146
	v_cmp_eq_u32_e64 s[4:5], 0, v146
	s_addc_u32 s59, s1, 0
	v_cmp_gt_i32_e64 s[6:7], s0, v146
	v_cmp_lt_u32_e64 s[8:9], s48, v0
	v_lshl_add_u32 v158, v157, 9, v146
	v_add_u32_e32 v147, 0x200, v146
	v_cmp_ne_u32_e64 s[10:11], v2, v157
	v_add_u32_e32 v160, s49, v159
	s_barrier
	s_branch .LBB0_712

; template <int TYPE>
; DI void attn_phase(const Params& P, int l, unsigned char* shm, const int rep, const bool cross = false) {
;     ...
;     for (;;) {
;         __syncthreads();
;         if (tid_ == 0) *sidx = atomicAdd(ctl + (l * 4 + (cross ? 3 : TYPE)) * 2 + rep, 1);
;         __syncthreads();
;         const int idx = *sidx;
;         if (idx >= (cross ? 256 : 512)) break;
.LBB0_712:
	s_and_saveexec_b64 s[0:1], s[4:5]
	s_cbranch_execz .LBB0_716
	s_mov_b64 s[62:63], exec
	v_mbcnt_lo_u32_b32 v0, s62, 0
	v_mbcnt_hi_u32_b32 v0, s63, v0
	v_cmp_eq_u32_e32 vcc, 0, v0
	s_and_saveexec_b64 s[60:61], vcc
	s_cbranch_execz .LBB0_715
	s_bcnt1_i32_b64 s16, s[62:63]
	s_waitcnt lgkmcnt(0)
	v_mov_b32_e32 v2, s16
	global_atomic_add v2, v1, v2, s[56:57] sc0

;     DI unsigned char* ws() const { return (unsigned char*)gp(35); }
; DI int fresh_tid(const Params& P) { int t = P.tid; asm volatile("" : "+v"(t)); return t; }
; template <int DQK, int MODE>
; DI void attn_body(const AttnArgs& a, char* lds) {
;     ...
;         } else { const int pos = (b - 16) * 1024 + lane * 16, row = pos / KROWB, within = pos - row * KROWB, c = (within ^ ksw(row)) >> 4;
; template <int TYPE>
; DI void attn_phase(const Params& P, int l, unsigned char* shm, const int rep, const bool cross = false) {
;     const int tid_ = fresh_tid(P);
;     unsigned char* ws = P.ws(); int* ctl = (int*)(ws + WS_CTL);
;     bf16_t* z = (bf16_t*)(ws + WS_Z); bf16_t* ckv = (bf16_t*)(ws + WS_H); bf16_t* cq = (bf16_t*)(ws + WS_CQ); bf16_t* o = (bf16_t*)(ws + WS_O);
;     int* sidx = (int*)(shm + ATT_IDX); float* tab = (float*)(shm + ATT_TAB);
;     for (;;) {
;         __syncthreads();
;         if (tid_ == 0) *sidx = atomicAdd(ctl + (l * 4 + (cross ? 3 : TYPE)) * 2 + rep, 1);
;         __syncthreads();
;         const int idx = *sidx;
.LBB0_760:
	v_mov_b32_e32 v132, v193
	v_mov_b32_e32 v0, s86
	s_waitcnt lgkmcnt(0)
	ds_read_b64 v[2:3], v0
	s_movk_i32 s60, 0xff00
	v_cmp_eq_u32_e64 s[0:1], 0, v132
	s_mov_b32 s47, 0x2aaaaaab
	s_movk_i32 s53, 0xfe80
	s_waitcnt lgkmcnt(0)
	v_readfirstlane_b32 s14, v2
	v_readfirstlane_b32 s12, v3
	s_add_u32 s15, s14, 0x1bc80000
	s_addc_u32 s22, s12, 0
	s_add_u32 s24, s14, 0x25c80000
	s_addc_u32 s25, s12, 0
	s_add_u32 s4, s14, s54
	s_addc_u32 s5, s12, s55
	s_add_u32 s6, s4, 0x29300008
	s_addc_u32 s7, s5, 0
	s_add_u32 s8, s14, 0x28c80000
	s_addc_u32 s9, s12, 0
	s_movk_i32 s56, 0xf1
	s_mov_b64 s[58:59], 0x100
	s_mov_b32 s61, -1
	s_barrier
	s_branch .LBB0_763

; template <int TYPE>
; DI void attn_phase(const Params& P, int l, unsigned char* shm, const int rep, const bool cross = false) {
;     ...
;     for (;;) {
;         __syncthreads();
;         if (tid_ == 0) *sidx = atomicAdd(ctl + (l * 4 + (cross ? 3 : TYPE)) * 2 + rep, 1);
;         __syncthreads();
;         const int idx = *sidx;
;         if (idx >= (cross ? 256 : 512)) break;
.LBB0_763:
	s_and_saveexec_b64 s[4:5], s[0:1]
	s_cbranch_execz .LBB0_767
	s_mov_b64 s[50:51], exec
	v_mbcnt_lo_u32_b32 v0, s50, 0
	v_mbcnt_hi_u32_b32 v0, s51, v0
	v_cmp_eq_u32_e32 vcc, 0, v0
	s_and_saveexec_b64 s[10:11], vcc
	s_cbranch_execz .LBB0_766
	s_bcnt1_i32_b64 s16, s[50:51]
	v_mov_b32_e32 v2, s16
	global_atomic_add v2, v1, v2, s[6:7] sc0

; template <int TYPE>
; DI void attn_phase(const Params& P, int l, unsigned char* shm, const int rep, const bool cross = false) {
;     const int tid_ = fresh_tid(P);
;     unsigned char* ws = P.ws(); int* ctl = (int*)(ws + WS_CTL);
;     bf16_t* z = (bf16_t*)(ws + WS_Z); bf16_t* ckv = (bf16_t*)(ws + WS_H); bf16_t* cq = (bf16_t*)(ws + WS_CQ); bf16_t* o = (bf16_t*)(ws + WS_O);
;     int* sidx = (int*)(shm + ATT_IDX); float* tab = (float*)(shm + ATT_TAB);
;     for (;;) {
;         __syncthreads();
;         if (tid_ == 0) *sidx = atomicAdd(ctl + (l * 4 + (cross ? 3 : TYPE)) * 2 + rep, 1);
;         __syncthreads();
;         const int idx = *sidx;
;         if (idx >= (cross ? 256 : 512)) break;
;         const bool sample = idx < 256; const int w = idx & 255, head = w >> 5, qbl = w & 31;
;         const int t0 = (sample ? 32 + qbl : qbl) * 256;
;         const int seqstart = sample ? 8192 : (qbl < 16 ? 0 : 4096), seqlen = sample ? 8192 : 4096;
;         AttnArgs a; a.tid = tid_; a.qpos0 = t0 - seqstart; a.seq = seqlen; a.tab = tab; a.rope = nullptr; a.K2 = nullptr; a.ldk2 = 0; a.map = 0; a.lam = 0.f; a.ga = nullptr; a.oscale = 1.f;
;         if constexpr (TYPE == 0) {
;             const float lam_init = l == 0 ? 0.2f : 0.35550907f;
;             a.lam = ((const float*)(ctl + 16))[l]; a.ga = P.in(12) + l * 128; a.oscale = 1.f - lam_init;
;             const float* rb = P.in(4);
;             for (int i = tid_; i < 257; i += NTHR) tab[i] = rb[t5_bucket(i - 128) * 8 + head] * LOG2E;
;             a.ldq = LDZ; a.ldk = LDZ; a.ldv = LDZ; a.ldo = 3072; a.C = 0.125f * LOG2E;
;             a.V = z + (size_t)seqstart * LDZ + ZC_AV + head * 128; a.O = o + (size_t)t0 * 3072 + head * 128;
;     ...
;             a.Q = z + (size_t)t0 * LDZ + ZC_AQ + head * 128; a.K = z + (size_t)seqstart * LDZ + ZC_AK + head * 128;
;             attn_body_dual(a, (char*)shm);
;     ...
; #pragma nounroll
;             for (int mp = 0; mp < 2; ++mp) { a.map = mp;
;                 a.Q = z + (size_t)t0 * LDZ + ZC_AQ + head * 128 + mp * 64; a.K = z + (size_t)seqstart * LDZ + ZC_AK + head * 128 + mp * 64;
;                 attn_body<64, 1>(a, (char*)shm); }
;     ...
;         } else if constexpr (TYPE == 1) {
;             a.rope = (const f32x2*)(ws + WS_ROPE);
;             a.Q = cq + (size_t)t0 * 1536 + head * 192; a.ldq = 1536; a.K = ckv + (size_t)seqstart * 2048 + head * 256; a.ldk = 2048;
.LBB0_793:
	s_and_b64 vcc, exec, s[0:1]
	s_movk_i32 s58, 0xe0
	s_mov_b64 s[60:61], 0x400
	s_cbranch_vccz .LBB0_292
	v_mov_b32_e32 v0, s86
	v_readlane_b32 s0, v242, 39
	s_waitcnt vmcnt(0)
	ds_read_b64 v[2:3], v0
	s_cmp_lg_u32 s0, 10
	s_cselect_b64 s[6:7], -1, 0
	s_cmp_eq_u32 s0, 10
	s_movk_i32 s0, 0x100
	s_cselect_b32 s12, s0, 0x200
	s_cselect_b32 s0, 6, 4
	s_or_b32 s4, s0, s52
	s_ashr_i32 s5, s4, 31
	s_waitcnt lgkmcnt(0)
	v_readfirstlane_b32 s15, v2
	v_readfirstlane_b32 s14, v3
	s_add_u32 s20, s15, 0x4c80000
	s_addc_u32 s22, s14, 0
	s_lshl_b64 s[4:5], s[4:5], 2
	s_add_u32 s4, s15, s4
	s_addc_u32 s5, s14, s5
	s_add_u32 s8, s4, 0x29300000
	s_addc_u32 s9, s5, 0
	s_add_u32 s24, s15, 0x29180000
	s_addc_u32 s25, s14, 0
	s_add_u32 s28, s15, 0x5c80000
	s_addc_u32 s29, s14, 0
	s_add_u32 s10, s15, 0x291a0400
	s_addc_u32 s11, s14, 0
	s_add_u32 s50, s15, 0x291a0000
	v_cmp_eq_u32_e64 s[0:1], 0, v193
	s_addc_u32 s51, s14, 0
	s_barrier
	s_branch .LBB0_798

; template <int TYPE>
; DI void attn_phase(const Params& P, int l, unsigned char* shm, const int rep, const bool cross = false) {
;     ...
;     for (;;) {
;         __syncthreads();
;         if (tid_ == 0) *sidx = atomicAdd(ctl + (l * 4 + (cross ? 3 : TYPE)) * 2 + rep, 1);
;         __syncthreads();
;         const int idx = *sidx;
;         if (idx >= (cross ? 256 : 512)) break;
.LBB0_798:
	s_and_saveexec_b64 s[4:5], s[0:1]
	s_cbranch_execz .LBB0_802
	s_mov_b64 s[54:55], exec
	v_mbcnt_lo_u32_b32 v0, s54, 0
	v_mbcnt_hi_u32_b32 v0, s55, v0
	v_cmp_eq_u32_e32 vcc, 0, v0
	s_and_saveexec_b64 s[52:53], vcc
	s_cbranch_execz .LBB0_801
	s_bcnt1_i32_b64 s16, s[54:55]
	v_mov_b32_e32 v2, s16
	global_atomic_add v2, v1, v2, s[8:9] sc0
